# attention: skip softmax/PV work of a wave's tile when every probability in it is exactly zero (row max more than 160 below the running max)
# speedup vs baseline: 1.0023x; 1.0023x over previous
; __device__ __forceinline__ unsigned cvt_pk_bf16(float lo, float hi) { f32x2 v = {lo, hi}; bf16x2v b = __builtin_convertvector(v, bf16x2v); return __builtin_bit_cast(unsigned, b); }
; __device__ __forceinline__ void attn_block(const Params& P, int bh, int qb, unsigned char* smem) {
;     ...
;             const float mn = m[u];
; #pragma unroll
;             for (int c = 0; c < 4; ++c)
; #pragma unroll
;                 for (int r = 0; r < 4; ++r) sa[u][c][r] = __builtin_amdgcn_exp2f(sa[u][c][r] - mn);
; #pragma unroll
;             for (int s2 = 0; s2 < 2; ++s2) {
;                 uint4 uu;
;                 uu.x = cvt_pk_bf16(sa[u][2 * s2][0], sa[u][2 * s2][1]); uu.y = cvt_pk_bf16(sa[u][2 * s2][2], sa[u][2 * s2][3]);
;                 uu.z = cvt_pk_bf16(sa[u][2 * s2 + 1][0], sa[u][2 * s2 + 1][1]); uu.w = cvt_pk_bf16(sa[u][2 * s2 + 1][2], sa[u][2 * s2 + 1][3]);
;                 pf[u][s2] = __builtin_bit_cast(bf16x8, uu);
;             }
;         }
;         {
;             uint2 vr[4][4];
;             tr_read_4c(sV, g, lr, vr);
; #pragma unroll
;             for (int c = 0; c < 4; ++c)
; #pragma unroll
;                 for (int s2 = 0; s2 < 2; ++s2) {
;                     const bf16x8 vf = tr_pair(vr[c][2 * s2], vr[c][2 * s2 + 1]);
;                     o[0][c] = __builtin_amdgcn_mfma_f32_16x16x32_bf16(vf, pf[0][s2], o[0][c], 0, 0, 0);
;                     o[1][c] = __builtin_amdgcn_mfma_f32_16x16x32_bf16(vf, pf[1][s2], o[1][c], 0, 0, 0);
;                 }
; #pragma unroll
;             for (int s2 = 0; s2 < 2; ++s2) {
;                 o[0][4] = __builtin_amdgcn_mfma_f32_16x16x32_bf16(vones, pf[0][s2], o[0][4], 0, 0, 0);
;                 o[1][4] = __builtin_amdgcn_mfma_f32_16x16x32_bf16(vones, pf[1][s2], o[1][4], 0, 0, 0);
;             }
;         }
;         __syncthreads();
.LBB0_708:
	v_cmp_lt_f32_e32 vcc, 0xc3200000, v197
	s_cbranch_vccnz .Lat_live
	s_waitcnt lgkmcnt(0)
	s_add_i32 s23, s23, -1
	s_sub_i32 s43, s43, 64
	s_barrier
	s_cmp_eq_u32 s23, -1
	s_cbranch_scc1 .LBB0_721
	s_branch .LBB0_709

; __device__ __forceinline__ void attn_block(const Params& P, int bh, int qb, unsigned char* smem) {
;     ...
;             float mx = -INFINITY;
; #pragma unroll
;             for (int c = 0; c < 4; ++c) {
;                 sa[u][c] -= ck[c];
;                 mx = fmaxf(mx, fmaxf(fmaxf(sa[u][c][0], sa[u][c][1]), fmaxf(sa[u][c][2], sa[u][c][3])));
;             }
;             mx = x4_max(mx);
;             if (__builtin_amdgcn_ballot_w64(mx > m[u]) != 0ull) {
;                 const float mn = fmaxf(m[u], mx);
;                 const float alpha = __builtin_amdgcn_exp2f(m[u] - mn);
;                 m[u] = mn;
; #pragma unroll
;                 for (int c = 0; c < 5; ++c) o[u][c] *= alpha;
;             }
.LBB0_717:
	s_nop 1
	v_max3_f32 v192, v102, v103, v104
	v_max3_f32 v193, v105, v98, v99
	v_max3_f32 v194, v100, v101, v110
	v_max3_f32 v195, v111, v112, v113
	v_max3_f32 v128, v106, v107, v108
	v_max3_f32 v192, v192, v193, v109
	v_max3_f32 v194, v194, v195, v128
	v_max_f32_e32 v192, v192, v194
	v_mov_b32_e32 v193, v192
	s_nop 1
	v_permlane32_swap_b32_e32 v192, v193
	s_nop 1
	v_max_f32_e32 v192, v192, v193
	v_mov_b32_e32 v193, v192
	s_nop 1
	v_permlane16_swap_b32_e32 v192, v193
	s_nop 1
	v_max_f32_e32 v192, v192, v193
	v_add_f32_e32 v197, v192, v196
	v_cmp_gt_f32_e32 vcc, v192, v187
	s_cbranch_vccz .LBB0_719
	v_max_f32_e32 v193, v187, v192
	v_sub_f32_e32 v192, v187, v193
	v_exp_f32_e32 v192, v192
	v_mov_b32_e32 v187, v193
	v_xor_b32_e32 v196, 0x80000000, v193
	v_pk_mul_f32 v[68:69], v[68:69], v[192:193] op_sel_hi:[1,0]
	v_pk_mul_f32 v[66:67], v[66:67], v[192:193] op_sel_hi:[1,0]
	v_pk_mul_f32 v[52:53], v[52:53], v[192:193] op_sel_hi:[1,0]
	v_pk_mul_f32 v[50:51], v[50:51], v[192:193] op_sel_hi:[1,0]
	v_pk_mul_f32 v[48:49], v[48:49], v[192:193] op_sel_hi:[1,0]
	v_pk_mul_f32 v[46:47], v[46:47], v[192:193] op_sel_hi:[1,0]
	v_pk_mul_f32 v[44:45], v[44:45], v[192:193] op_sel_hi:[1,0]
	v_pk_mul_f32 v[42:43], v[42:43], v[192:193] op_sel_hi:[1,0]
	v_pk_mul_f32 v[80:81], v[80:81], v[192:193] op_sel_hi:[1,0]
	v_pk_mul_f32 v[78:79], v[78:79], v[192:193] op_sel_hi:[1,0]
.LBB0_719:
	v_max3_f32 v192, v86, v87, v88
	v_max3_f32 v193, v89, v82, v83
	v_max3_f32 v194, v84, v85, v94
	v_max3_f32 v195, v95, v96, v97
	v_max3_f32 v128, v90, v91, v92
	v_max3_f32 v192, v192, v193, v93
	v_max3_f32 v194, v194, v195, v128
	v_max_f32_e32 v192, v192, v194
	v_mov_b32_e32 v193, v192
	s_nop 1
	v_permlane32_swap_b32_e32 v192, v193
	s_nop 1
	v_max_f32_e32 v192, v192, v193
	v_mov_b32_e32 v193, v192
	s_nop 1
	v_permlane16_swap_b32_e32 v192, v193
	s_nop 1
	v_max_f32_e32 v192, v192, v193
	v_add_f32_e32 v194, v192, v230
	v_max_f32_e32 v197, v197, v194
	v_cmp_gt_f32_e32 vcc, v192, v2
	s_cbranch_vccz .LBB0_708
	v_max_f32_e32 v193, v2, v192
	v_sub_f32_e32 v192, v2, v193
	v_exp_f32_e32 v192, v192
	v_mov_b32_e32 v2, v193
	v_xor_b32_e32 v230, 0x80000000, v193
	v_pk_mul_f32 v[36:37], v[36:37], v[192:193] op_sel_hi:[1,0]
	v_pk_mul_f32 v[34:35], v[34:35], v[192:193] op_sel_hi:[1,0]
	v_pk_mul_f32 v[32:33], v[32:33], v[192:193] op_sel_hi:[1,0]
	v_pk_mul_f32 v[30:31], v[30:31], v[192:193] op_sel_hi:[1,0]
	v_pk_mul_f32 v[28:29], v[28:29], v[192:193] op_sel_hi:[1,0]
	v_pk_mul_f32 v[26:27], v[26:27], v[192:193] op_sel_hi:[1,0]
	v_pk_mul_f32 v[24:25], v[24:25], v[192:193] op_sel_hi:[1,0]
	v_pk_mul_f32 v[22:23], v[22:23], v[192:193] op_sel_hi:[1,0]
	v_pk_mul_f32 v[40:41], v[40:41], v[192:193] op_sel_hi:[1,0]
	v_pk_mul_f32 v[38:39], v[38:39], v[192:193] op_sel_hi:[1,0]
	s_branch .LBB0_708
